# attention block tail: counted lgkmcnt waits in the two drain P.V blocks (as in the main loop)
# baseline (speedup 1.0000x reference)
.LBB0_411:
	s_ashr_i32 s6, s26, 31
	s_lshr_b32 s6, s6, 26
	s_add_i32 s6, s6, s26
	s_addk_i32 s6, 0xff
	s_andn2_b32 s6, s6, 63
	v_add_u32_e32 v98, s6, v201
	v_add_u32_e32 v100, s6, v211
	v_ashrrev_i32_e32 v99, 31, v98
	v_ashrrev_i32_e32 v101, 31, v100
	v_lshlrev_b64 v[106:107], 8, v[98:99]
	v_lshlrev_b64 v[108:109], 8, v[100:101]
	v_lshl_add_u64 v[98:99], s[24:25], 0, v[106:107]
	v_lshl_add_u64 v[100:101], s[24:25], 0, v[108:109]
	v_lshl_add_u64 v[106:107], s[22:23], 0, v[106:107]
	v_lshl_add_u64 v[108:109], s[22:23], 0, v[108:109]
	v_lshl_add_u64 v[98:99], v[98:99], 0, v[0:1]
	v_lshl_add_u64 v[102:103], v[100:101], 0, v[0:1]
	v_lshl_add_u64 v[106:107], v[106:107], 0, v[0:1]
	v_lshl_add_u64 v[110:111], v[108:109], 0, v[0:1]
	global_load_dwordx4 v[98:101], v[98:99], off
	s_nop 0
	global_load_dwordx4 v[102:105], v[102:103], off
	s_nop 0
	global_load_dwordx4 v[106:109], v[106:107], off
	s_nop 0
	global_load_dwordx4 v[110:113], v[110:111], off
	v_or_b32_e32 v130, s48, v212
	v_ashrrev_i32_e32 v131, 31, v130
	v_lshlrev_b64 v[130:131], 8, v[130:131]
	v_lshl_add_u64 v[130:131], s[14:15], 0, v[130:131]
	v_mov_b32_e32 v201, v1
	v_lshl_add_u64 v[130:131], v[130:131], 0, v[200:201]
	global_load_dwordx4 v[158:161], v[130:131], off
	global_load_dwordx4 v[154:157], v[130:131], off offset:32
	global_load_dwordx4 v[150:153], v[130:131], off offset:64
	global_load_dwordx4 v[146:149], v[130:131], off offset:96
	global_load_dwordx4 v[142:145], v[130:131], off offset:128
	global_load_dwordx4 v[138:141], v[130:131], off offset:160
	global_load_dwordx4 v[134:137], v[130:131], off offset:192
	s_nop 0
	global_load_dwordx4 v[130:133], v[130:131], off offset:224
	v_exp_f32_e32 v189, v114
	v_add_f32_e32 v114, 0, v175
	v_add_f32_e32 v114, v177, v114
	v_add_f32_e32 v114, v173, v114
	v_add_f32_e32 v114, v176, v114
	v_add_f32_e32 v114, v171, v114
	v_add_f32_e32 v114, v174, v114
	v_add_f32_e32 v114, v170, v114
	v_add_f32_e32 v114, v172, v114
	v_add_f32_e32 v114, v164, v114
	v_add_f32_e32 v114, v167, v114
	v_add_f32_e32 v114, v163, v114
	v_add_f32_e32 v114, v165, v114
	v_exp_f32_e32 v0, v128
	v_add_f32_e32 v114, v162, v114
	v_exp_f32_e32 v128, v129
	v_add_f32_e32 v114, v169, v114
	v_exp_f32_e32 v126, v126
	v_add_f32_e32 v114, v166, v114
	v_exp_f32_e32 v127, v127
	v_add_f32_e32 v114, v168, v114
	v_exp_f32_e32 v124, v124
	v_add_f32_e32 v114, v0, v114
	v_exp_f32_e32 v125, v125
	v_add_f32_e32 v114, v128, v114
	v_exp_f32_e32 v129, v122
	v_add_f32_e32 v114, v126, v114
	v_exp_f32_e32 v179, v123
	v_add_f32_e32 v114, v127, v114
	v_exp_f32_e32 v180, v120
	v_add_f32_e32 v114, v124, v114
	v_exp_f32_e32 v184, v121
	v_add_f32_e32 v114, v125, v114
	v_exp_f32_e32 v185, v118
	v_add_f32_e32 v114, v129, v114
	v_exp_f32_e32 v186, v119
	v_add_f32_e32 v114, v179, v114
	v_exp_f32_e32 v187, v116
	v_add_f32_e32 v114, v180, v114
	v_exp_f32_e32 v188, v117
	v_add_f32_e32 v114, v184, v114
	v_add_f32_e32 v114, v185, v114
	v_exp_f32_e32 v190, v115
	v_add_f32_e32 v114, v186, v114
	v_add_f32_e32 v114, v187, v114
	v_add_f32_e32 v114, v188, v114
	v_add_f32_e32 v114, v189, v114
	v_add_f32_e32 v181, v190, v114
	v_mov_b32_e32 v183, v181
	v_cvt_pk_bf16_f32 v114, v175, v177
	v_cvt_pk_bf16_f32 v115, v173, v176
	v_cvt_pk_bf16_f32 v116, v171, v174
	v_cvt_pk_bf16_f32 v117, v170, v172
	v_cvt_pk_bf16_f32 v118, v164, v167
	v_cvt_pk_bf16_f32 v119, v163, v165
	v_cvt_pk_bf16_f32 v120, v162, v169
	v_cvt_pk_bf16_f32 v121, v166, v168
	v_cvt_pk_bf16_f32 v122, v0, v128
	v_cvt_pk_bf16_f32 v123, v126, v127
	v_cvt_pk_bf16_f32 v124, v124, v125
	v_cvt_pk_bf16_f32 v125, v129, v179
	s_nop 1
	v_permlane32_swap_b32_e32 v181, v183
	v_permlane32_swap_b32_e32 v114, v116
	v_permlane32_swap_b32_e32 v115, v117
	v_permlane32_swap_b32_e32 v118, v120
	v_permlane32_swap_b32_e32 v119, v121
	v_permlane32_swap_b32_e32 v122, v124
	v_permlane32_swap_b32_e32 v123, v125
	v_cvt_pk_bf16_f32 v184, v180, v184
	v_cvt_pk_bf16_f32 v185, v185, v186
	v_cvt_pk_bf16_f32 v186, v187, v188
	v_cvt_pk_bf16_f32 v187, v189, v190
	s_nop 0
	v_permlane32_swap_b32_e32 v184, v186
	v_permlane32_swap_b32_e32 v185, v187
	ds_read_b64_tr_b16 v[126:127], v209 offset:0
	ds_read_b64_tr_b16 v[128:129], v209 offset:0x800
	ds_read_b64_tr_b16 v[162:163], v209 offset:0x1000
	ds_read_b64_tr_b16 v[164:165], v209 offset:0x1800
	ds_read_b64_tr_b16 v[166:167], v209 offset:0x2000
	ds_read_b64_tr_b16 v[168:169], v209 offset:0x2800
	ds_read_b64_tr_b16 v[170:171], v209 offset:0x3000
	ds_read_b64_tr_b16 v[172:173], v209 offset:0x3800
	s_nop 0
	s_waitcnt lgkmcnt(6)
	v_mfma_f32_32x32x16_bf16 v[66:81], v[114:117], v[126:129], v[66:81]
	ds_read_b64_tr_b16 v[126:127], v209 offset:0x200
	ds_read_b64_tr_b16 v[128:129], v209 offset:0xa00
	s_waitcnt lgkmcnt(6)
	v_mfma_f32_32x32x16_bf16 v[66:81], v[118:121], v[162:165], v[66:81]
	ds_read_b64_tr_b16 v[162:163], v209 offset:0x1200
	ds_read_b64_tr_b16 v[164:165], v209 offset:0x1a00
	s_waitcnt lgkmcnt(6)
	v_mfma_f32_32x32x16_bf16 v[66:81], v[122:125], v[166:169], v[66:81]
	ds_read_b64_tr_b16 v[166:167], v209 offset:0x2200
	ds_read_b64_tr_b16 v[168:169], v209 offset:0x2a00
	ds_read_b64_tr_b16 v[174:175], v209 offset:0x3200
	ds_read_b64_tr_b16 v[176:177], v209 offset:0x3a00
	s_waitcnt lgkmcnt(8)
	v_mfma_f32_32x32x16_bf16 v[66:81], v[184:187], v[170:173], v[66:81]
	s_waitcnt lgkmcnt(6)
	v_mfma_f32_32x32x16_bf16 v[34:49], v[114:117], v[126:129], v[34:49]
	ds_read_b64_tr_b16 v[126:127], v209 offset:0x400
	ds_read_b64_tr_b16 v[128:129], v209 offset:0xc00
	s_waitcnt lgkmcnt(6)
	v_mfma_f32_32x32x16_bf16 v[34:49], v[118:121], v[162:165], v[34:49]
	ds_read_b64_tr_b16 v[162:163], v209 offset:0x1400
	ds_read_b64_tr_b16 v[164:165], v209 offset:0x1c00
	s_waitcnt lgkmcnt(6)
	v_mfma_f32_32x32x16_bf16 v[34:49], v[122:125], v[166:169], v[34:49]
	ds_read_b64_tr_b16 v[166:167], v209 offset:0x2400
	ds_read_b64_tr_b16 v[168:169], v209 offset:0x2c00
	ds_read_b64_tr_b16 v[170:171], v209 offset:0x3400
	ds_read_b64_tr_b16 v[172:173], v209 offset:0x3c00
	s_waitcnt lgkmcnt(8)
	v_mfma_f32_32x32x16_bf16 v[34:49], v[184:187], v[174:177], v[34:49]
	s_waitcnt lgkmcnt(6)
	v_mfma_f32_32x32x16_bf16 v[18:33], v[114:117], v[126:129], v[18:33]
	ds_read_b64_tr_b16 v[126:127], v209 offset:0x600
	ds_read_b64_tr_b16 v[128:129], v209 offset:0xe00
	s_waitcnt lgkmcnt(6)
	v_mfma_f32_32x32x16_bf16 v[18:33], v[118:121], v[162:165], v[18:33]
	ds_read_b64_tr_b16 v[162:163], v209 offset:0x1600
	ds_read_b64_tr_b16 v[164:165], v209 offset:0x1e00
	s_waitcnt lgkmcnt(6)
	v_mfma_f32_32x32x16_bf16 v[18:33], v[122:125], v[166:169], v[18:33]
	ds_read_b64_tr_b16 v[166:167], v209 offset:0x2600
	ds_read_b64_tr_b16 v[168:169], v209 offset:0x2e00
	ds_read_b64_tr_b16 v[188:189], v209 offset:0x3600
	ds_read_b64_tr_b16 v[190:191], v209 offset:0x3e00
	s_waitcnt lgkmcnt(8)
	v_mfma_f32_32x32x16_bf16 v[18:33], v[184:187], v[170:173], v[18:33]
	s_waitcnt lgkmcnt(6)
	v_mfma_f32_32x32x16_bf16 v[2:17], v[114:117], v[126:129], v[2:17]
	s_ashr_i32 s49, s48, 31
	v_mov_b32_e32 v0, v206
	s_lshl_b64 s[6:7], s[48:49], 11
	s_add_u32 s6, s50, s6
	v_lshlrev_b32_e32 v114, 7, v0
	v_lshlrev_b32_e32 v115, 2, v0
	s_waitcnt lgkmcnt(4)
	v_mfma_f32_32x32x16_bf16 v[2:17], v[118:121], v[162:165], v[2:17]
	s_addc_u32 s7, s51, s7
	s_mov_b64 s[50:51], -1
	s_and_b64 vcc, exec, s[4:5]
	v_and_b32_e32 v179, 28, v115
	v_and_b32_e32 v180, 0xfffffc00, v114
	s_waitcnt lgkmcnt(2)
	v_mfma_f32_32x32x16_bf16 v[2:17], v[122:125], v[166:169], v[2:17]
	s_waitcnt lgkmcnt(0)
	v_mfma_f32_32x32x16_bf16 v[2:17], v[184:187], v[188:191], v[2:17]
	s_cbranch_vccz .LBB0_413
	v_or_b32_e32 v114, v180, v179
	v_add_u32_e32 v115, 0x2000, v180
	v_add_u32_e32 v117, 0x4000, v180
	v_add_u32_e32 v119, 0x6000, v180
	v_lshlrev_b32_e32 v114, 1, v114
	v_or_b32_e32 v116, v115, v179
	v_or_b32_e32 v118, v117, v179
	v_or_b32_e32 v120, v119, v179
	v_lshlrev_b32_e32 v116, 1, v116
	v_lshlrev_b32_e32 v118, 1, v118
	v_lshlrev_b32_e32 v120, 1, v120
	global_load_dwordx2 v[176:177], v114, s[6:7]
	global_load_dwordx2 v[174:175], v116, s[6:7]
	global_load_dwordx2 v[172:173], v118, s[6:7]
	global_load_dwordx2 v[170:171], v120, s[6:7]
	v_or_b32_e32 v114, 32, v179
	v_or_b32_e32 v116, v114, v180
	v_or_b32_e32 v118, v115, v114
	v_or_b32_e32 v120, v117, v114
	v_or_b32_e32 v114, v119, v114
	v_lshlrev_b32_e32 v116, 1, v116
	v_lshlrev_b32_e32 v114, 1, v114
	v_lshlrev_b32_e32 v118, 1, v118
	v_lshlrev_b32_e32 v120, 1, v120
	global_load_dwordx2 v[168:169], v116, s[6:7]
	global_load_dwordx2 v[166:167], v118, s[6:7]
	global_load_dwordx2 v[164:165], v120, s[6:7]
	global_load_dwordx2 v[162:163], v114, s[6:7]
	v_or_b32_e32 v114, 64, v179
	v_or_b32_e32 v116, v114, v180
	v_or_b32_e32 v118, v115, v114
	v_or_b32_e32 v120, v117, v114
	v_or_b32_e32 v114, v119, v114
	v_lshlrev_b32_e32 v116, 1, v116
	v_lshlrev_b32_e32 v114, 1, v114
	v_lshlrev_b32_e32 v118, 1, v118
	v_lshlrev_b32_e32 v120, 1, v120
	global_load_dwordx2 v[128:129], v116, s[6:7]
	global_load_dwordx2 v[126:127], v118, s[6:7]
	global_load_dwordx2 v[124:125], v120, s[6:7]
	global_load_dwordx2 v[122:123], v114, s[6:7]
	v_or_b32_e32 v114, 0x60, v179
	v_or_b32_e32 v116, v114, v180
	v_or_b32_e32 v115, v115, v114
	v_or_b32_e32 v117, v117, v114
	v_or_b32_e32 v114, v119, v114
	v_lshlrev_b32_e32 v116, 1, v116
	v_lshlrev_b32_e32 v115, 1, v115
	v_lshlrev_b32_e32 v117, 1, v117
	v_lshlrev_b32_e32 v114, 1, v114
	global_load_dwordx2 v[120:121], v116, s[6:7]
	global_load_dwordx2 v[118:119], v115, s[6:7]
	s_nop 0
	global_load_dwordx2 v[116:117], v117, s[6:7]
	s_nop 0
	global_load_dwordx2 v[114:115], v114, s[6:7]
	s_mov_b64 s[50:51], 0

.LBB0_420:
	v_cndmask_b32_e64 v114, v114, v182, s[4:5]
	v_mul_f32_e32 v114, 0xbe0293ee, v114
	v_fmamk_f32 v50, v50, 0x3e0293ee, v114
	v_fmamk_f32 v51, v51, 0x3e0293ee, v114
	v_exp_f32_e32 v50, v50
	v_fmamk_f32 v52, v52, 0x3e0293ee, v114
	v_fmamk_f32 v119, v65, 0x3e0293ee, v114
	v_exp_f32_e32 v65, v51
	v_fmamk_f32 v53, v53, 0x3e0293ee, v114
	v_exp_f32_e32 v51, v52
	v_fmamk_f32 v54, v54, 0x3e0293ee, v114
	v_fmamk_f32 v55, v55, 0x3e0293ee, v114
	v_fmamk_f32 v56, v56, 0x3e0293ee, v114
	v_fmamk_f32 v57, v57, 0x3e0293ee, v114
	v_fmamk_f32 v58, v58, 0x3e0293ee, v114
	v_fmamk_f32 v59, v59, 0x3e0293ee, v114
	v_fmamk_f32 v60, v60, 0x3e0293ee, v114
	v_fmamk_f32 v115, v61, 0x3e0293ee, v114
	v_fmamk_f32 v116, v62, 0x3e0293ee, v114
	v_fmamk_f32 v117, v63, 0x3e0293ee, v114
	v_fmamk_f32 v118, v64, 0x3e0293ee, v114
	v_fmamk_f32 v82, v82, 0x3e0293ee, v114
	v_fmamk_f32 v83, v83, 0x3e0293ee, v114
	v_fmamk_f32 v84, v84, 0x3e0293ee, v114
	v_fmamk_f32 v85, v85, 0x3e0293ee, v114
	v_fmamk_f32 v86, v86, 0x3e0293ee, v114
	v_fmamk_f32 v87, v87, 0x3e0293ee, v114
	v_fmamk_f32 v88, v88, 0x3e0293ee, v114
	v_fmamk_f32 v89, v89, 0x3e0293ee, v114
	v_fmamk_f32 v90, v90, 0x3e0293ee, v114
	v_fmamk_f32 v91, v91, 0x3e0293ee, v114
	v_fmamk_f32 v92, v92, 0x3e0293ee, v114
	v_fmamk_f32 v93, v93, 0x3e0293ee, v114
	v_fmamk_f32 v94, v94, 0x3e0293ee, v114
	v_exp_f32_e32 v64, v53
	v_fmamk_f32 v95, v95, 0x3e0293ee, v114
	v_fmamk_f32 v96, v96, 0x3e0293ee, v114
	v_fmac_f32_e32 v114, 0x3e0293ee, v97
	v_exp_f32_e32 v52, v54
	v_exp_f32_e32 v97, v114
	v_add_f32_e32 v114, 0, v50
	v_exp_f32_e32 v63, v55
	v_add_f32_e32 v114, v65, v114
	v_exp_f32_e32 v53, v56
	v_add_f32_e32 v114, v51, v114
	v_exp_f32_e32 v62, v57
	v_add_f32_e32 v114, v64, v114
	v_exp_f32_e32 v54, v58
	v_add_f32_e32 v114, v52, v114
	v_exp_f32_e32 v61, v59
	v_add_f32_e32 v114, v63, v114
	v_exp_f32_e32 v55, v60
	v_add_f32_e32 v114, v53, v114
	v_exp_f32_e32 v60, v115
	v_add_f32_e32 v114, v62, v114
	v_exp_f32_e32 v56, v116
	v_add_f32_e32 v114, v54, v114
	v_exp_f32_e32 v59, v117
	v_add_f32_e32 v114, v61, v114
	v_exp_f32_e32 v57, v118
	v_add_f32_e32 v114, v55, v114
	v_exp_f32_e32 v58, v119
	v_add_f32_e32 v114, v60, v114
	v_exp_f32_e32 v82, v82
	v_add_f32_e32 v114, v56, v114
	v_exp_f32_e32 v83, v83
	v_add_f32_e32 v114, v59, v114
	v_exp_f32_e32 v84, v84
	v_add_f32_e32 v114, v57, v114
	v_exp_f32_e32 v85, v85
	v_add_f32_e32 v114, v58, v114
	v_exp_f32_e32 v86, v86
	v_add_f32_e32 v114, v82, v114
	v_exp_f32_e32 v87, v87
	v_add_f32_e32 v114, v83, v114
	v_exp_f32_e32 v88, v88
	v_add_f32_e32 v114, v84, v114
	v_exp_f32_e32 v89, v89
	v_add_f32_e32 v114, v85, v114
	v_exp_f32_e32 v90, v90
	v_add_f32_e32 v114, v86, v114
	v_exp_f32_e32 v91, v91
	v_add_f32_e32 v114, v87, v114
	v_exp_f32_e32 v92, v92
	v_add_f32_e32 v114, v88, v114
	v_exp_f32_e32 v93, v93
	v_add_f32_e32 v114, v89, v114
	v_exp_f32_e32 v94, v94
	v_add_f32_e32 v114, v90, v114
	v_exp_f32_e32 v95, v95
	v_add_f32_e32 v114, v91, v114
	v_exp_f32_e32 v96, v96
	v_add_f32_e32 v114, v92, v114
	v_add_f32_e32 v114, v93, v114
	v_add_f32_e32 v114, v94, v114
	v_add_f32_e32 v114, v95, v114
	v_add_f32_e32 v114, v96, v114
	v_add_f32_e32 v182, v97, v114
	v_mov_b32_e32 v183, v182
	v_cvt_pk_bf16_f32 v50, v50, v65
	v_cvt_pk_bf16_f32 v51, v51, v64
	v_cvt_pk_bf16_f32 v52, v52, v63
	v_cvt_pk_bf16_f32 v53, v53, v62
	v_cvt_pk_bf16_f32 v54, v54, v61
	v_cvt_pk_bf16_f32 v55, v55, v60
	v_cvt_pk_bf16_f32 v56, v56, v59
	v_cvt_pk_bf16_f32 v57, v57, v58
	v_cvt_pk_bf16_f32 v58, v82, v83
	v_cvt_pk_bf16_f32 v59, v84, v85
	v_cvt_pk_bf16_f32 v60, v86, v87
	v_cvt_pk_bf16_f32 v61, v88, v89
	v_cvt_pk_bf16_f32 v62, v90, v91
	v_cvt_pk_bf16_f32 v63, v92, v93
	v_cvt_pk_bf16_f32 v64, v94, v95
	v_cvt_pk_bf16_f32 v65, v96, v97
	s_nop 1
	v_permlane32_swap_b32_e32 v182, v183
	v_permlane32_swap_b32_e32 v50, v52
	v_permlane32_swap_b32_e32 v51, v53
	v_permlane32_swap_b32_e32 v54, v56
	v_permlane32_swap_b32_e32 v55, v57
	v_permlane32_swap_b32_e32 v58, v60
	v_permlane32_swap_b32_e32 v59, v61
	v_permlane32_swap_b32_e32 v62, v64
	v_permlane32_swap_b32_e32 v63, v65
	v_or_b32_e32 v82, v180, v179
	v_add_u32_e32 v83, 0x2000, v180
	v_add_u32_e32 v85, 0x4000, v180
	v_add_u32_e32 v87, 0x6000, v180
	v_lshlrev_b32_e32 v82, 1, v82
	v_or_b32_e32 v84, v83, v179
	v_or_b32_e32 v86, v85, v179
	v_or_b32_e32 v88, v87, v179
	v_lshlrev_b32_e32 v84, 1, v84
	v_lshlrev_b32_e32 v86, 1, v86
	v_lshlrev_b32_e32 v88, 1, v88
	global_load_dwordx2 v[176:177], v82, s[6:7]
	global_load_dwordx2 v[174:175], v84, s[6:7]
	global_load_dwordx2 v[172:173], v86, s[6:7]
	global_load_dwordx2 v[170:171], v88, s[6:7]
	v_or_b32_e32 v82, 32, v179
	v_or_b32_e32 v84, v82, v180
	v_or_b32_e32 v86, v83, v82
	v_or_b32_e32 v88, v85, v82
	v_or_b32_e32 v82, v87, v82
	v_lshlrev_b32_e32 v84, 1, v84
	v_lshlrev_b32_e32 v82, 1, v82
	v_lshlrev_b32_e32 v86, 1, v86
	v_lshlrev_b32_e32 v88, 1, v88
	global_load_dwordx2 v[168:169], v84, s[6:7]
	global_load_dwordx2 v[166:167], v86, s[6:7]
	global_load_dwordx2 v[164:165], v88, s[6:7]
	global_load_dwordx2 v[162:163], v82, s[6:7]
	v_or_b32_e32 v82, 64, v179
	v_or_b32_e32 v84, v82, v180
	v_or_b32_e32 v86, v83, v82
	v_or_b32_e32 v88, v85, v82
	v_or_b32_e32 v82, v87, v82
	v_lshlrev_b32_e32 v84, 1, v84
	v_lshlrev_b32_e32 v82, 1, v82
	v_lshlrev_b32_e32 v86, 1, v86
	v_lshlrev_b32_e32 v88, 1, v88
	global_load_dwordx2 v[128:129], v84, s[6:7]
	global_load_dwordx2 v[126:127], v86, s[6:7]
	global_load_dwordx2 v[124:125], v88, s[6:7]
	global_load_dwordx2 v[122:123], v82, s[6:7]
	v_or_b32_e32 v82, 0x60, v179
	v_or_b32_e32 v84, v82, v180
	v_lshlrev_b32_e32 v84, 1, v84
	v_or_b32_e32 v83, v83, v82
	v_or_b32_e32 v85, v85, v82
	v_or_b32_e32 v82, v87, v82
	v_lshlrev_b32_e32 v83, 1, v83
	v_lshlrev_b32_e32 v85, 1, v85
	v_lshlrev_b32_e32 v82, 1, v82
	global_load_dwordx2 v[120:121], v84, s[6:7]
	global_load_dwordx2 v[118:119], v83, s[6:7]
	global_load_dwordx2 v[116:117], v85, s[6:7]
	global_load_dwordx2 v[114:115], v82, s[6:7]
	v_add_f32_e32 v186, v182, v183
	v_fmac_f32_e32 v186, v181, v178
	ds_read_b64_tr_b16 v[82:83], v209 offset:0x4000
	ds_read_b64_tr_b16 v[84:85], v209 offset:0x4800
	ds_read_b64_tr_b16 v[86:87], v209 offset:0x5000
	ds_read_b64_tr_b16 v[88:89], v209 offset:0x5800
	ds_read_b64_tr_b16 v[90:91], v209 offset:0x6000
	ds_read_b64_tr_b16 v[92:93], v209 offset:0x6800
	ds_read_b64_tr_b16 v[94:95], v209 offset:0x7000
	ds_read_b64_tr_b16 v[96:97], v209 offset:0x7800
	s_nop 0
	s_waitcnt lgkmcnt(6)
	v_mfma_f32_32x32x16_bf16 v[66:81], v[50:53], v[82:85], v[66:81]
	ds_read_b64_tr_b16 v[82:83], v209 offset:0x4200
	ds_read_b64_tr_b16 v[84:85], v209 offset:0x4a00
	s_waitcnt lgkmcnt(6)
	v_mfma_f32_32x32x16_bf16 v[66:81], v[54:57], v[86:89], v[66:81]
	ds_read_b64_tr_b16 v[86:87], v209 offset:0x5200
	ds_read_b64_tr_b16 v[88:89], v209 offset:0x5a00
	s_waitcnt lgkmcnt(6)
	v_mfma_f32_32x32x16_bf16 v[66:81], v[58:61], v[90:93], v[66:81]
	ds_read_b64_tr_b16 v[90:91], v209 offset:0x6200
	ds_read_b64_tr_b16 v[92:93], v209 offset:0x6a00
	ds_read_b64_tr_b16 v[178:179], v209 offset:0x7200
	ds_read_b64_tr_b16 v[180:181], v209 offset:0x7a00
	s_waitcnt lgkmcnt(8)
	v_mfma_f32_32x32x16_bf16 v[66:81], v[62:65], v[94:97], v[66:81]
	s_waitcnt lgkmcnt(6)
	v_mfma_f32_32x32x16_bf16 v[34:49], v[50:53], v[82:85], v[34:49]
	ds_read_b64_tr_b16 v[82:83], v209 offset:0x4400
	ds_read_b64_tr_b16 v[84:85], v209 offset:0x4c00
	s_waitcnt lgkmcnt(6)
	v_mfma_f32_32x32x16_bf16 v[34:49], v[54:57], v[86:89], v[34:49]
	ds_read_b64_tr_b16 v[86:87], v209 offset:0x5400
	ds_read_b64_tr_b16 v[88:89], v209 offset:0x5c00
	s_waitcnt lgkmcnt(6)
	v_mfma_f32_32x32x16_bf16 v[34:49], v[58:61], v[90:93], v[34:49]
	ds_read_b64_tr_b16 v[90:91], v209 offset:0x6400
	ds_read_b64_tr_b16 v[92:93], v209 offset:0x6c00
	ds_read_b64_tr_b16 v[94:95], v209 offset:0x7400
	ds_read_b64_tr_b16 v[96:97], v209 offset:0x7c00
	s_waitcnt lgkmcnt(8)
	v_mfma_f32_32x32x16_bf16 v[34:49], v[62:65], v[178:181], v[34:49]
	s_waitcnt lgkmcnt(6)
	v_mfma_f32_32x32x16_bf16 v[18:33], v[50:53], v[82:85], v[18:33]
	ds_read_b64_tr_b16 v[82:83], v209 offset:0x4600
	ds_read_b64_tr_b16 v[84:85], v209 offset:0x4e00
	s_waitcnt lgkmcnt(6)
	v_mfma_f32_32x32x16_bf16 v[18:33], v[54:57], v[86:89], v[18:33]
	ds_read_b64_tr_b16 v[86:87], v209 offset:0x5600
	ds_read_b64_tr_b16 v[88:89], v209 offset:0x5e00
	s_waitcnt lgkmcnt(6)
	v_mfma_f32_32x32x16_bf16 v[18:33], v[58:61], v[90:93], v[18:33]
	ds_read_b64_tr_b16 v[90:91], v209 offset:0x6600
	ds_read_b64_tr_b16 v[92:93], v209 offset:0x6e00
	ds_read_b64_tr_b16 v[182:183], v209 offset:0x7600
	ds_read_b64_tr_b16 v[184:185], v209 offset:0x7e00
	s_waitcnt lgkmcnt(8)
	v_mfma_f32_32x32x16_bf16 v[18:33], v[62:65], v[94:97], v[18:33]
	s_waitcnt lgkmcnt(6)
	v_mfma_f32_32x32x16_bf16 v[2:17], v[50:53], v[82:85], v[2:17]
	v_mov_b32_e32 v181, v186
	s_waitcnt lgkmcnt(4)
	v_mfma_f32_32x32x16_bf16 v[2:17], v[54:57], v[86:89], v[2:17]
	s_waitcnt lgkmcnt(2)
	v_mfma_f32_32x32x16_bf16 v[2:17], v[58:61], v[90:93], v[2:17]
	s_waitcnt lgkmcnt(0)
	v_mfma_f32_32x32x16_bf16 v[2:17], v[62:65], v[182:185], v[2:17]
